# m3 phase: compression-MLP rows moved to workgroups 128-255 (two rounds each) so they run beside the SSD state pass on workgroups 0-127 instead of before it
# baseline (speedup 1.0000x reference)
.LBB0_706:
	s_or_b64 exec, exec, s[6:7]
	v_mov_b32_e32 v20, v1
	s_mov_b64 s[4:5], s[0:1]
	s_barrier
	s_load_dwordx2 s[8:9], s[4:5], 0xd8
	v_readfirstlane_b32 s2, v20
	s_ashr_i32 s4, s2, 6
	v_readlane_b32 s2, v243, 2
	s_sub_i32 s2, s2, 0x400
	s_cmp_lt_i32 s2, 0
	s_cselect_b32 s2, 0x800, s2
	s_add_i32 s2, s4, s2
	s_mov_b64 s[6:7], s[0:1]
	s_cmpk_gt_i32 s2, 0x7ff
	s_cbranch_scc1 .LBB0_727
	s_waitcnt lgkmcnt(0)
	s_add_u32 s10, s8, 0x15c00000
	s_load_dwordx2 s[6:7], s[6:7], 0x78
	s_addc_u32 s11, s9, 0
	s_add_u32 s12, s8, 0x15c80000
	s_addc_u32 s13, s9, 0
	v_and_b32_e32 v2, 63, v20
	v_lshlrev_b32_e32 v3, 1, v20
	s_add_u32 s20, s8, 0x15800610
	v_lshlrev_b32_e32 v10, 2, v2
	v_and_b32_e32 v24, 48, v3
	s_addc_u32 s21, s9, 0
	s_lshl_b32 s4, s4, 2
	v_readlane_b32 s5, v243, 22
	s_waitcnt lgkmcnt(0)
	v_lshl_add_u64 v[2:3], s[6:7], 0, v[10:11]
	v_bfe_u32 v21, v20, 4, 2
	v_and_b32_e32 v22, 15, v20
	v_bfe_u32 v23, v20, 5, 1
	v_and_b32_e32 v25, 7, v20
	s_add_i32 s14, s5, s4
	s_sub_i32 s14, s14, 0x1000
	v_lshl_add_u64 v[12:13], v[2:3], 0, s[56:57]
	s_branch .LBB0_709
.LBB0_708:
	v_readlane_b32 s4, v243, 55
	s_addk_i32 s2, 0x400
	s_addk_i32 s14, 0x1000
	s_cmpk_gt_i32 s2, 0x7ff
	s_cbranch_scc1 .LBB0_727
